# output phase: per-head group-norm gain/bias vectors loaded once before the trip loop (8 of 25 VMEM instructions per wave and trip removed; trip-top waits recounted)
# baseline (speedup 1.0000x reference)
; __device__ __forceinline__ void phase_out(const Params& p, unsigned char* shm) {
;     ...
;     const int half = wid >> 2, nt = wid & 3, th = tid & 255, crow = th >> 3, cseg = (th & 7) * 8;
;     bf16_t* base = (bf16_t*)shm + half * 7 * TILE;
;     bf16_t* SbT = base; bf16_t* UTt = base + TILE; bf16_t* Qt = base + 2 * TILE; bf16_t* AQt = base + 3 * TILE; bf16_t* YVt = base + 4 * TILE; bf16_t* PVt = base + 5 * TILE; bf16_t* GBt = base + 6 * TILE;
;     u32x4 g[7][2];
;     auto gload = [&](int pr) {
;         const int item = 2 * pr + half, h = item & 15, row0 = (item >> 4) * 64; const size_t cb = (size_t)item * 4096;
; #pragma unroll
;         for (int i = 0; i < 2; ++i) { const int r = crow + 32 * i; const size_t o = cb + r * 64 + cseg;
;             g[0][i] = *(const u32x4*)(p.Z + (size_t)(row0 + r) * LDZ + ZC_S + h * 64 + cseg);
;             g[1][i] = *(const u32x4*)(p.UTG + o); g[2][i] = *(const u32x4*)(p.QG + o); g[3][i] = *(const u32x4*)(p.AQBG + o); g[4][i] = *(const u32x4*)(p.YVG + o);
;             g[5][i] = *(const u32x4*)(p.PV + ((size_t)(row0 + r) * 16 + h) * 64 + cseg);
;             g[6][i] = *(const u32x4*)(p.Z + (size_t)(row0 + r) * LDZ + ZC_GB + h * 64 + cseg); }
;     };
;     if ((int)blockIdx.x < NPAIR) gload(blockIdx.x);
;     for (int pr = blockIdx.x; pr < NPAIR; pr += gridDim.x) {
;         const int item = 2 * pr + half, h = item & 15, row0 = (item >> 4) * 64;
;         const float rk = p.PRK[(size_t)(row0 + 16 * nt + fr) * 16 + h];
;         f32x4 gng[4], gnb[4];
; #pragma unroll
;         for (int mv = 0; mv < 4; ++mv) { gng[mv] = *(const f32x4*)(p.gn_g + h * 64 + 16 * mv + 4 * fq); gnb[mv] = *(const f32x4*)(p.gn_b + h * 64 + 16 * mv + 4 * fq); }
; #pragma unroll
;         for (int a = 0; a < 7; ++a)
; #pragma unroll
;             for (int i = 0; i < 2; ++i) *(u32x4*)(base + a * TILE + (crow + 32 * i) * LD + cseg) = g[a][i];
;         { const int npr = pr + (int)gridDim.x; gload(npr < NPAIR ? npr : pr); }
.LBB0_496:
	s_or_b64 exec, exec, s[2:3]
	s_cmpk_gt_i32 s40, 0x10ff
	s_barrier
	s_cbranch_scc1 .LBB0_499
	s_load_dwordx2 s[2:3], s[0:1], 0xb8
	v_lshrrev_b32_e32 v109, 8, v133
	v_lshl_add_u32 v104, s40, 1, v109
	s_waitcnt vmcnt(2)
	v_lshlrev_b32_e32 v0, 2, v104
	v_and_b32_e32 v111, 31, v164
	v_and_b32_e32 v26, 0xffffffc0, v0
	v_or_b32_e32 v20, v26, v111
	s_movk_i32 s10, 0x3a00
	s_waitcnt lgkmcnt(0)
	v_mov_b64_e32 v[0:1], s[2:3]
	v_lshlrev_b32_e32 v2, 7, v104
	v_and_b32_e32 v56, 56, v131
	v_mov_b32_e32 v107, 0
	v_mad_i64_i32 v[0:1], s[4:5], v20, s10, v[0:1]
	v_and_b32_e32 v106, 0x780, v2
	v_lshlrev_b32_e32 v58, 1, v56
	v_mov_b32_e32 v59, v107
	v_lshl_add_u64 v[0:1], v[0:1], 0, v[106:107]
	v_lshl_add_u64 v[24:25], v[0:1], 0, v[58:59]
	s_movk_i32 s11, 0x1000
	v_add_co_u32_e32 v0, vcc, s11, v24
	v_ashrrev_i32_e32 v105, 31, v104
	s_nop 0
	v_addc_co_u32_e32 v1, vcc, 0, v25, vcc
	s_movk_i32 s20, 0x3000
	v_lshlrev_b64 v[32:33], 12, v[104:105]
	s_load_dwordx8 s[12:19], s[0:1], 0xe0
	v_add_co_u32_e32 v34, vcc, s20, v24
	v_or_b32_e32 v105, 32, v111
	s_nop 0
	v_addc_co_u32_e32 v35, vcc, 0, v25, vcc
	v_or_b32_e32 v48, v26, v105
	v_mov_b64_e32 v[24:25], s[2:3]
	s_load_dwordx2 s[4:5], s[0:1], 0x100
	s_load_dwordx2 s[6:7], s[0:1], 0x128
	v_mad_i64_i32 v[24:25], s[8:9], v48, s10, v[24:25]
	v_ashrrev_i32_e32 v21, 31, v20
	v_lshl_add_u64 v[24:25], v[24:25], 0, v[106:107]
	v_lshl_or_b32 v108, v111, 6, v56
	v_lshlrev_b64 v[20:21], 11, v[20:21]
	v_ashrrev_i32_e32 v49, 31, v48
	v_lshl_add_u64 v[52:53], v[24:25], 0, v[58:59]
	v_or_b32_e32 v4, v32, v108
	v_mov_b32_e32 v5, v33
	s_waitcnt lgkmcnt(0)
	v_lshl_add_u64 v[20:21], s[12:13], 0, v[20:21]
	v_lshl_or_b32 v110, v105, 6, v56
	v_add_co_u32_e32 v36, vcc, s11, v52
	v_lshlrev_b64 v[48:49], 11, v[48:49]
	v_lshlrev_b64 v[16:17], 1, v[4:5]
	v_lshl_add_u64 v[20:21], v[20:21], 0, v[106:107]
	v_or_b32_e32 v32, v32, v110
	v_addc_co_u32_e32 v37, vcc, 0, v53, vcc
	v_lshl_add_u64 v[48:49], s[12:13], 0, v[48:49]
	v_lshl_add_u64 v[4:5], s[4:5], 0, v[16:17]
	s_waitcnt vmcnt(0)
	v_lshl_add_u64 v[8:9], s[14:15], 0, v[16:17]
	v_lshl_add_u64 v[12:13], s[16:17], 0, v[16:17]
	v_lshl_add_u64 v[16:17], s[18:19], 0, v[16:17]
	v_lshl_add_u64 v[20:21], v[20:21], 0, v[58:59]
	v_lshlrev_b64 v[44:45], 1, v[32:33]
	v_lshl_add_u64 v[48:49], v[48:49], 0, v[106:107]
	v_add_co_u32_e32 v52, vcc, s20, v52
	global_load_dwordx4 v[0:3], v[0:1], off offset:2048
	v_lshl_add_u64 v[32:33], s[4:5], 0, v[44:45]
	global_load_dwordx4 v[4:7], v[4:5], off
	v_lshl_add_u64 v[40:41], s[16:17], 0, v[44:45]
	global_load_dwordx4 v[8:11], v[8:9], off
	v_lshl_add_u64 v[48:49], v[48:49], 0, v[58:59]
	global_load_dwordx4 v[12:15], v[12:13], off
	v_addc_co_u32_e32 v53, vcc, 0, v53, vcc
	global_load_dwordx4 v[16:19], v[16:17], off
	v_lshrrev_b32_e32 v60, 2, v133
	global_load_dwordx4 v[20:23], v[20:21], off
	s_nop 0
	global_load_dwordx4 v[24:27], v[34:35], off offset:256
	global_load_dwordx4 v[28:31], v[36:37], off offset:2048
	v_lshl_add_u64 v[36:37], s[14:15], 0, v[44:45]
	v_lshl_add_u64 v[44:45], s[18:19], 0, v[44:45]
	global_load_dwordx4 v[32:35], v[32:33], off
	s_load_dwordx4 s[24:27], s[0:1], 0x98
	global_load_dwordx4 v[36:39], v[36:37], off
	s_mov_b32 s8, 0xfc00
	global_load_dwordx4 v[40:43], v[40:41], off
	v_bfe_u32 v59, v133, 4, 2
	global_load_dwordx4 v[44:47], v[44:45], off
	v_and_or_b32 v119, v60, 48, v161
	global_load_dwordx4 v[48:51], v[48:49], off
	v_mad_u32_u24 v57, v109, s8, 0
	global_load_dwordx4 v[52:55], v[52:53], off offset:256
	v_mul_u32_u24_e32 v60, 0x90, v119
	v_lshlrev_b32_e32 v122, 3, v59
	v_lshlrev_b32_e32 v106, 4, v59
	v_add_u32_e32 v58, v57, v58
	v_add3_u32 v123, v57, v60, v122
	v_add_u32_e32 v57, v57, v106
	v_mul_u32_u24_e32 v59, 0x90, v111
	v_mul_u32_u24_e32 v60, 0x90, v161
	v_readlane_b32 s8, v244, 3
	s_waitcnt lgkmcnt(0)
	v_lshl_add_u64 v[112:113], s[24:25], 0, v[106:107]
	v_lshl_add_u64 v[114:115], s[26:27], 0, v[106:107]
	v_lshl_add_u32 v124, v109, 2, s8
	s_lshl_b32 s21, s38, 3
	s_lshl_b32 s22, s38, 1
	v_add_u32_e32 v125, v58, v59
	v_lshlrev_b32_e32 v116, 1, v56
	v_add_u32_e32 v126, v57, v60
	v_mov_b32_e32 v127, 0x3a27c5ac
	s_mov_b32 s23, 0x800000
	v_mbcnt_hi_u32_b32 v134, -1, v129
	s_mov_b32 s8, s40
	v_and_b32_e32 v136, 15, v104
	v_lshlrev_b32_e32 v204, 8, v136
	v_mov_b32_e32 v205, 0
	v_lshl_add_u64 v[206:207], v[112:113], 0, v[204:205]
	v_lshl_add_u64 v[208:209], v[114:115], 0, v[204:205]
	global_load_dwordx4 v[172:175], v[206:207], off
	global_load_dwordx4 v[176:179], v[208:209], off
	global_load_dwordx4 v[180:183], v[206:207], off offset:64
	global_load_dwordx4 v[184:187], v[208:209], off offset:64
	global_load_dwordx4 v[188:191], v[206:207], off offset:128
	global_load_dwordx4 v[192:195], v[208:209], off offset:128
	global_load_dwordx4 v[196:199], v[206:207], off offset:192
	global_load_dwordx4 v[200:203], v[208:209], off offset:192
	s_waitcnt vmcnt(0)
; __device__ __forceinline__ void phase_out(const Params& p, unsigned char* shm) {
;     ...
;     for (int pr = blockIdx.x; pr < NPAIR; pr += gridDim.x) {
;         const int item = 2 * pr + half, h = item & 15, row0 = (item >> 4) * 64;
;         const float rk = p.PRK[(size_t)(row0 + 16 * nt + fr) * 16 + h];
;         f32x4 gng[4], gnb[4];
; #pragma unroll
;         for (int mv = 0; mv < 4; ++mv) { gng[mv] = *(const f32x4*)(p.gn_g + h * 64 + 16 * mv + 4 * fq); gnb[mv] = *(const f32x4*)(p.gn_b + h * 64 + 16 * mv + 4 * fq); }
; #pragma unroll
;         for (int a = 0; a < 7; ++a)
; #pragma unroll
;             for (int i = 0; i < 2; ++i) *(u32x4*)(base + a * TILE + (crow + 32 * i) * LD + cseg) = g[a][i];
;         { const int npr = pr + (int)gridDim.x; gload(npr < NPAIR ? npr : pr); }
.LBB0_498:
	v_and_b32_e32 v135, 0xffffffc0, v124
	v_or_b32_e32 v56, v135, v119
	v_ashrrev_i32_e32 v57, 31, v56
	s_add_i32 s24, s8, s38
	v_and_b32_e32 v136, 15, v104
	v_lshlrev_b64 v[56:57], 6, v[56:57]
	s_cmpk_lt_i32 s24, 0x1100
	v_lshl_add_u64 v[56:57], s[6:7], 0, v[56:57]
	v_lshlrev_b32_e32 v106, 2, v136
	s_cselect_b64 s[26:27], -1, 0
	v_lshl_add_u64 v[56:57], v[56:57], 0, v[106:107]
	v_lshlrev_b32_e32 v106, 8, v136
	s_and_b64 vcc, s[26:27], exec
	global_load_dword v118, v[56:57], off
	s_cselect_b32 s8, s24, s8
	v_mov_b32_e32 v80, v172
	v_mov_b32_e32 v81, v173
	v_mov_b32_e32 v82, v174
	v_mov_b32_e32 v83, v175
	v_mov_b32_e32 v84, v176
	v_mov_b32_e32 v85, v177
	v_mov_b32_e32 v86, v178
	v_mov_b32_e32 v87, v179
	v_mov_b32_e32 v72, v180
	v_mov_b32_e32 v73, v181
	v_mov_b32_e32 v74, v182
	v_mov_b32_e32 v75, v183
	v_mov_b32_e32 v76, v184
	v_mov_b32_e32 v77, v185
	v_mov_b32_e32 v78, v186
	v_mov_b32_e32 v79, v187
	v_mov_b32_e32 v64, v188
	v_mov_b32_e32 v65, v189
	v_mov_b32_e32 v66, v190
	v_mov_b32_e32 v67, v191
	v_mov_b32_e32 v68, v192
	v_mov_b32_e32 v69, v193
	v_mov_b32_e32 v70, v194
	v_mov_b32_e32 v71, v195
	v_mov_b32_e32 v56, v196
	v_mov_b32_e32 v57, v197
	v_mov_b32_e32 v58, v198
	v_mov_b32_e32 v59, v199
	v_mov_b32_e32 v60, v200
	v_mov_b32_e32 v61, v201
	v_mov_b32_e32 v62, v202
	v_mov_b32_e32 v63, v203
	s_waitcnt vmcnt(16)
	ds_write_b128 v125, v[0:3]
	s_waitcnt vmcnt(9)
	ds_write_b128 v125, v[28:31] offset:4608
	ds_write_b128 v125, v[4:7] offset:9216
	s_waitcnt vmcnt(8)
	ds_write_b128 v125, v[32:35] offset:13824
	ds_write_b128 v125, v[8:11] offset:18432
	s_waitcnt vmcnt(7)
	ds_write_b128 v125, v[36:39] offset:23040
	ds_write_b128 v125, v[12:15] offset:27648
	s_waitcnt vmcnt(6)
	ds_write_b128 v125, v[40:43] offset:32256
	ds_write_b128 v125, v[16:19] offset:36864
	s_waitcnt vmcnt(5)
	ds_write_b128 v125, v[44:47] offset:41472
	ds_write_b128 v125, v[20:23] offset:46080
	s_waitcnt vmcnt(4)
	ds_write_b128 v125, v[48:51] offset:50688
	ds_write_b128 v125, v[24:27] offset:55296
	s_waitcnt vmcnt(3)
	ds_write_b128 v125, v[52:55] offset:59904
	v_lshl_add_u32 v0, s8, 1, v109
	v_lshlrev_b32_e32 v1, 2, v0
	v_and_b32_e32 v30, 0xffffffc0, v1
	v_ashrrev_i32_e32 v1, 31, v0
	v_lshlrev_b64 v[32:33], 12, v[0:1]
	v_or_b32_e32 v20, v30, v111
	v_mov_b64_e32 v[28:29], s[2:3]
	v_lshlrev_b32_e32 v0, 7, v0
	v_mad_i64_i32 v[2:3], s[8:9], v20, s10, v[28:29]
	v_and_b32_e32 v106, 0x780, v0
	v_mov_b32_e32 v117, v107
	v_lshl_add_u64 v[0:1], v[2:3], 0, v[106:107]
	v_lshl_add_u64 v[24:25], v[0:1], 0, v[116:117]
	v_add_co_u32_e64 v0, s[8:9], s11, v24
	v_or_b32_e32 v48, v30, v105
	s_nop 0
	v_addc_co_u32_e64 v1, s[8:9], 0, v25, s[8:9]
	v_add_co_u32_e64 v24, s[8:9], s20, v24
	v_ashrrev_i32_e32 v21, 31, v20
	s_nop 0
	v_addc_co_u32_e64 v25, s[8:9], 0, v25, s[8:9]
	v_mad_i64_i32 v[28:29], s[8:9], v48, s10, v[28:29]
	v_lshl_add_u64 v[28:29], v[28:29], 0, v[106:107]
	v_ashrrev_i32_e32 v49, 31, v48
	v_lshl_add_u64 v[52:53], v[28:29], 0, v[116:117]
	v_lshlrev_b64 v[20:21], 11, v[20:21]
	v_add_co_u32_e64 v28, s[8:9], s11, v52
	v_lshlrev_b64 v[48:49], 11, v[48:49]
	v_or_b32_e32 v4, v32, v108
	v_mov_b32_e32 v5, v33
	v_lshl_add_u64 v[20:21], s[12:13], 0, v[20:21]
	v_or_b32_e32 v32, v32, v110
	v_addc_co_u32_e64 v29, s[8:9], 0, v53, s[8:9]
	v_lshl_add_u64 v[48:49], s[12:13], 0, v[48:49]
	v_lshlrev_b64 v[16:17], 1, v[4:5]
	v_lshl_add_u64 v[20:21], v[20:21], 0, v[106:107]
	v_lshlrev_b64 v[44:45], 1, v[32:33]
	v_lshl_add_u64 v[48:49], v[48:49], 0, v[106:107]
	v_add_co_u32_e64 v52, s[8:9], s20, v52
	v_lshl_add_u64 v[4:5], s[4:5], 0, v[16:17]
	v_lshl_add_u64 v[8:9], s[14:15], 0, v[16:17]
	v_lshl_add_u64 v[12:13], s[16:17], 0, v[16:17]
	v_lshl_add_u64 v[16:17], s[18:19], 0, v[16:17]
	v_lshl_add_u64 v[20:21], v[20:21], 0, v[116:117]
	v_lshl_add_u64 v[32:33], s[4:5], 0, v[44:45]
	v_lshl_add_u64 v[36:37], s[14:15], 0, v[44:45]
	v_lshl_add_u64 v[40:41], s[16:17], 0, v[44:45]
	v_lshl_add_u64 v[44:45], s[18:19], 0, v[44:45]
	v_lshl_add_u64 v[48:49], v[48:49], 0, v[116:117]
	v_addc_co_u32_e64 v53, s[8:9], 0, v53, s[8:9]
	global_load_dwordx4 v[0:3], v[0:1], off offset:2048
	v_add_u32_e32 v106, 0x9000, v123
	global_load_dwordx4 v[4:7], v[4:5], off
	v_add_u32_e32 v120, v123, v122
	global_load_dwordx4 v[8:11], v[8:9], off
	v_and_b32_e32 v137, 64, v134
	global_load_dwordx4 v[12:15], v[12:13], off
	v_add_u32_e32 v137, 64, v137
	global_load_dwordx4 v[16:19], v[16:17], off
	v_add_u32_e32 v124, s21, v124
	global_load_dwordx4 v[20:23], v[20:21], off
	v_add_u32_e32 v104, s22, v104
	global_load_dwordx4 v[24:27], v[24:25], off offset:256
	s_nop 0
	global_load_dwordx4 v[28:31], v[28:29], off offset:2048
	s_nop 0
	global_load_dwordx4 v[32:35], v[32:33], off
	s_nop 0
	global_load_dwordx4 v[36:39], v[36:37], off
	s_nop 0
	global_load_dwordx4 v[40:43], v[40:41], off
	s_nop 0
	global_load_dwordx4 v[44:47], v[44:45], off
	s_nop 0
	global_load_dwordx4 v[48:51], v[48:49], off
	s_nop 0
	global_load_dwordx4 v[52:55], v[52:53], off offset:256
	s_waitcnt lgkmcnt(0)
	s_barrier
; __device__ __forceinline__ f32x4 ld_bf4(const bf16_t* p) { const u32x2 u = *(const u32x2*)p; return (f32x4){bf_lo(u.x), bf_hi(u.x), bf_lo(u.y), bf_hi(u.y)}; }
; #define MFMA16(a, b, c) __builtin_amdgcn_mfma_f32_16x16x32_bf16(a, b, c, 0, 0, 0)
; __device__ __forceinline__ void phase_out(const Params& p, unsigned char* shm) {
;     ...
;         const int trow = 16 * nt + fr;
;         f32x4 acc[4];
; #pragma unroll
;         for (int mv = 0; mv < 4; ++mv) acc[mv] = ld_bf4(YVt + trow * LD + 16 * mv + 4 * fq);
; #pragma unroll
;         for (int ks = 0; ks < 2; ++ks) {
;             const bf16x8 bq = ldfrag(Qt, LD, 16 * nt, 32 * ks, fr, fq), ba = ldfrag(AQt, LD, 16 * nt, 32 * ks, fr, fq);
; #pragma unroll
;             for (int mv = 0; mv < 4; ++mv) {
;                 acc[mv] = MFMA16(ldfrag(SbT, LD, 16 * mv, 32 * ks, fr, fq), bq, acc[mv]);
;                 acc[mv] = MFMA16(ldfrag(UTt, LD, 16 * mv, 32 * ks, fr, fq), ba, acc[mv]);
;             }
;         }
;         float s = 0.f;
; #pragma unroll
;         for (int mv = 0; mv < 4; ++mv) s += (acc[mv][0] + acc[mv][1]) + (acc[mv][2] + acc[mv][3]);
;         s += __shfl_xor(s, 16); s += __shfl_xor(s, 32);
;         const float mean = s * (1.0f / 64.0f);
;         float q = 0.f;
; #pragma unroll
;         for (int mv = 0; mv < 4; ++mv) { const f32x4 d = acc[mv] - mean; q += (d[0] * d[0] + d[1] * d[1]) + (d[2] * d[2] + d[3] * d[3]); }
;         q += __shfl_xor(q, 16); q += __shfl_xor(q, 32);
;         const float rstd = rsqrtf(q * (1.0f / 64.0f) + 64e-5f);
	ds_read2_b64 v[88:91], v106 offset1:4
	ds_read2_b64 v[96:99], v106 offset0:8 offset1:12
	ds_read_b128 v[138:141], v120 offset:18432
	ds_read_b128 v[142:145], v120 offset:27648
	ds_read_b128 v[146:149], v126
	s_waitcnt lgkmcnt(4)
	v_lshlrev_b32_e32 v92, 16, v88
	v_and_b32_e32 v93, 0xffff0000, v88
	v_lshlrev_b32_e32 v94, 16, v89
	v_and_b32_e32 v95, 0xffff0000, v89
	v_lshlrev_b32_e32 v88, 16, v90
	v_and_b32_e32 v89, 0xffff0000, v90
	s_waitcnt lgkmcnt(0)
	v_mfma_f32_16x16x32_bf16 v[92:95], v[146:149], v[138:141], v[92:95]
	ds_read_b128 v[146:149], v126 offset:9216
	v_lshlrev_b32_e32 v90, 16, v91
	v_and_b32_e32 v91, 0xffff0000, v91
	s_waitcnt lgkmcnt(0)
	v_mfma_f32_16x16x32_bf16 v[92:95], v[146:149], v[142:145], v[92:95]
	ds_read_b128 v[146:149], v126 offset:2304
	v_lshlrev_b32_e32 v100, 16, v96
	v_and_b32_e32 v101, 0xffff0000, v96
	s_waitcnt lgkmcnt(0)
	v_mfma_f32_16x16x32_bf16 v[88:91], v[146:149], v[138:141], v[88:91]
	ds_read_b128 v[146:149], v126 offset:11520
	v_lshlrev_b32_e32 v102, 16, v97
	v_and_b32_e32 v103, 0xffff0000, v97
	s_waitcnt lgkmcnt(0)
	v_mfma_f32_16x16x32_bf16 v[88:91], v[146:149], v[142:145], v[88:91]
	ds_read_b128 v[146:149], v126 offset:4608
	v_lshlrev_b32_e32 v96, 16, v98
	v_and_b32_e32 v97, 0xffff0000, v98
	s_waitcnt lgkmcnt(0)
	v_mfma_f32_16x16x32_bf16 v[100:103], v[146:149], v[138:141], v[100:103]
	ds_read_b128 v[146:149], v126 offset:13824
	v_lshlrev_b32_e32 v98, 16, v99
	v_and_b32_e32 v99, 0xffff0000, v99
	s_waitcnt lgkmcnt(0)
	v_mfma_f32_16x16x32_bf16 v[146:149], v[146:149], v[142:145], v[100:103]
	s_nop 2
	ds_read_b128 v[100:103], v126 offset:6912
	s_waitcnt lgkmcnt(0)
	v_mfma_f32_16x16x32_bf16 v[96:99], v[100:103], v[138:141], v[96:99]
	ds_read_b128 v[100:103], v126 offset:16128
	s_waitcnt lgkmcnt(0)
	v_mfma_f32_16x16x32_bf16 v[138:141], v[100:103], v[142:145], v[96:99]
	ds_read_b128 v[142:145], v120 offset:18496
	ds_read_b128 v[150:153], v120 offset:27712
	s_nop 2
	ds_read_b128 v[96:99], v126 offset:64
	s_waitcnt lgkmcnt(0)
	v_mfma_f32_16x16x32_bf16 v[92:95], v[96:99], v[142:145], v[92:95]
	ds_read_b128 v[96:99], v126 offset:9280
	s_waitcnt lgkmcnt(0)
	v_mfma_f32_16x16x32_bf16 v[100:103], v[96:99], v[150:153], v[92:95]
	s_nop 4
	ds_read_b128 v[92:95], v126 offset:2368
	s_nop 1
	v_mov_b32_e32 v120, v101
	s_waitcnt lgkmcnt(0)
	v_mfma_f32_16x16x32_bf16 v[88:91], v[92:95], v[142:145], v[88:91]
	ds_read_b128 v[92:95], v126 offset:11584
	v_mov_b32_e32 v121, v102
	s_waitcnt lgkmcnt(0)
	v_mfma_f32_16x16x32_bf16 v[96:99], v[92:95], v[150:153], v[88:91]
	s_nop 3
	ds_read_b128 v[88:91], v126 offset:4672
	ds_read_b128 v[92:95], v126 offset:13888
	s_waitcnt lgkmcnt(1)
	v_mfma_f32_16x16x32_bf16 v[88:91], v[88:91], v[142:145], v[146:149]
	s_waitcnt lgkmcnt(0)
	v_mfma_f32_16x16x32_bf16 v[92:95], v[92:95], v[150:153], v[88:91]
	s_nop 5
	ds_read_b128 v[88:91], v126 offset:6976
	s_waitcnt lgkmcnt(0)
	v_mfma_f32_16x16x32_bf16 v[88:91], v[88:91], v[142:145], v[138:141]
	s_nop 2
	ds_read_b128 v[138:141], v126 offset:16192
	v_add_f32_e32 v142, v94, v95
	s_waitcnt lgkmcnt(0)
	v_mfma_f32_16x16x32_bf16 v[88:91], v[138:141], v[150:153], v[88:91]
	v_mov_b32_e32 v138, v100
	v_mov_b32_e32 v139, v103
	v_pk_add_f32 v[120:121], v[120:121], v[138:139]
	v_mov_b32_e32 v138, v97
	v_mov_b32_e32 v139, v98
	v_mov_b32_e32 v140, v96
	v_mov_b32_e32 v141, v99
	v_pk_add_f32 v[138:139], v[138:139], v[140:141]
	v_add_f32_e32 v120, v120, v121
	v_pk_add_f32 v[138:139], v[138:139], v[138:139] op_sel:[0,1] op_sel_hi:[1,0]
	v_add_f32_e32 v120, 0, v120
	v_add_f32_e32 v140, v92, v93
	v_mov_b32_e32 v121, v88
	v_mov_b32_e32 v139, v89
	v_mov_b32_e32 v141, v90
	v_mov_b32_e32 v143, v91
	v_pk_add_f32 v[120:121], v[120:121], v[138:139]
	v_pk_add_f32 v[138:139], v[140:141], v[142:143]
	s_nop 0
	v_pk_add_f32 v[120:121], v[120:121], v[138:139]
	s_nop 0
	v_add_f32_e32 v120, v120, v121
	v_xor_b32_e32 v121, 16, v134
	v_cmp_lt_i32_e64 s[8:9], v121, v137
	s_nop 1
	v_cndmask_b32_e64 v121, v134, v121, s[8:9]
	v_lshlrev_b32_e32 v144, 2, v121
	ds_bpermute_b32 v121, v144, v120
	s_waitcnt lgkmcnt(0)
	v_add_f32_e32 v120, v120, v121
	v_xor_b32_e32 v121, 32, v134
	v_cmp_lt_i32_e64 s[8:9], v121, v137
	s_nop 1
	v_cndmask_b32_e64 v121, v134, v121, s[8:9]
	v_lshlrev_b32_e32 v137, 2, v121
	ds_bpermute_b32 v121, v137, v120
	s_waitcnt lgkmcnt(0)
	v_add_f32_e32 v145, v120, v121
	v_fmamk_f32 v121, v145, 0xbc800000, v101
	v_fmamk_f32 v120, v145, 0xbc800000, v100
	v_fmamk_f32 v103, v145, 0xbc800000, v103
	v_fmac_f32_e32 v102, 0xbc800000, v145
	v_pk_mul_f32 v[100:101], v[102:103], v[102:103]
	v_pk_mul_f32 v[138:139], v[120:121], v[120:121]
	v_fmamk_f32 v99, v145, 0xbc800000, v99
	v_pk_mov_b32 v[140:141], v[138:139], v[100:101] op_sel:[1,0]
	v_mov_b32_e32 v139, v101
	v_pk_add_f32 v[100:101], v[140:141], v[138:139]
	v_fmac_f32_e32 v98, 0xbc800000, v145
	v_pk_add_f32 v[138:139], v[100:101], v[100:101] op_sel_hi:[0,1]
	v_fmamk_f32 v101, v145, 0xbc800000, v97
	v_fmamk_f32 v100, v145, 0xbc800000, v96
	v_pk_mul_f32 v[96:97], v[98:99], v[98:99]
	v_pk_mul_f32 v[140:141], v[100:101], v[100:101]
	v_fmac_f32_e32 v94, 0xbc800000, v145
	v_pk_mov_b32 v[142:143], v[140:141], v[96:97] op_sel:[1,0]
	v_mov_b32_e32 v141, v97
	v_pk_add_f32 v[96:97], v[142:143], v[140:141]
	v_fmamk_f32 v95, v145, 0xbc800000, v95
	v_pk_add_f32 v[140:141], v[96:97], v[96:97] op_sel_hi:[0,1]
	v_fmamk_f32 v96, v145, 0xbc800000, v92
	v_fmamk_f32 v97, v145, 0xbc800000, v93
	v_mul_f32_e32 v92, v96, v96
	v_pk_fma_f32 v[92:93], v[96:97], v[96:97], v[92:93] op_sel_hi:[1,1,0]
	v_fmamk_f32 v91, v145, 0xbc800000, v91
	v_mul_f32_e32 v92, v94, v94
	v_pk_fma_f32 v[142:143], v[94:95], v[94:95], v[92:93] op_sel_hi:[1,1,0]
	v_fmamk_f32 v90, v145, 0xbc800000, v90
	v_fmamk_f32 v89, v145, 0xbc800000, v89
	v_fmac_f32_e32 v88, 0xbc800000, v145
	v_mul_f32_e32 v92, v88, v88
	v_mul_f32_e32 v142, v89, v89
	v_mul_f32_e32 v138, v90, v90
	v_mul_f32_e32 v140, v91, v91
	v_pk_add_f32 v[92:93], v[92:93], v[142:143]
	v_pk_add_f32 v[138:139], v[138:139], v[140:141]
	s_nop 0
	v_pk_add_f32 v[92:93], v[92:93], v[138:139]
	s_nop 0
	v_add_f32_e32 v92, v92, v93
	ds_bpermute_b32 v93, v144, v92
	s_waitcnt lgkmcnt(0)
; __device__ __forceinline__ float silu_f(float x) { return x * __builtin_amdgcn_rcpf(1.0f + __builtin_amdgcn_exp2f(-1.44269504089f * x)); }
; __device__ __forceinline__ f32x4 ld_bf4(const bf16_t* p) { const u32x2 u = *(const u32x2*)p; return (f32x4){bf_lo(u.x), bf_hi(u.x), bf_lo(u.y), bf_hi(u.y)}; }
; __device__ __forceinline__ void st_bf4(bf16_t* p, f32x4 v) { u32x2 u; u.x = pk_bf16(v[0], v[1]); u.y = pk_bf16(v[2], v[3]); *(u32x2*)p = u; }
; __device__ __forceinline__ void phase_out(const Params& p, unsigned char* shm) {
;     ...
;         const float rstd = rsqrtf(q * (1.0f / 64.0f) + 64e-5f);
; #pragma unroll
;         for (int mv = 0; mv < 4; ++mv) {
;             const int vch = 16 * mv + 4 * fq;
;             const f32x4 vmx = ld_bf4(PVt + trow * LD + vch), gb = ld_bf4(GBt + trow * LD + vch);
;             f32x4 o = (acc[mv] - mean) * rstd * gng[mv] + gnb[mv] + rk * vmx;
; #pragma unroll
;             for (int e = 0; e < 4; ++e) o[e] *= silu_f(gb[e]);
;             st_bf4(YVt + trow * LD + vch, o);
;         }
	v_add_f32_e32 v92, v92, v93
	ds_bpermute_b32 v93, v137, v92
	v_add_u32_e32 v137, 0xd800, v123
	ds_read2_b64 v[142:145], v137 offset1:4
	s_waitcnt lgkmcnt(1)
	v_add_f32_e32 v92, v92, v93
	v_fmamk_f32 v92, v92, 0x3c800000, v127
	v_cmp_gt_f32_e64 s[8:9], s23, v92
	v_mul_f32_e32 v93, 0x4b800000, v92
	s_nop 0
	v_cndmask_b32_e64 v92, v92, v93, s[8:9]
	v_rsq_f32_e32 v92, v92
	s_nop 0
	v_mul_f32_e32 v93, 0x45800000, v92
	v_cndmask_b32_e64 v92, v92, v93, s[8:9]
	v_add_u32_e32 v93, 0xb000, v123
	v_pk_mul_f32 v[120:121], v[120:121], v[92:93] op_sel_hi:[1,0]
	v_pk_mul_f32 v[102:103], v[102:103], v[92:93] op_sel_hi:[1,0]
	s_waitcnt vmcnt(14)
	v_pk_fma_f32 v[80:81], v[80:81], v[120:121], v[84:85]
	s_waitcnt lgkmcnt(0)
	v_lshlrev_b32_e32 v84, 16, v142
	v_and_b32_e32 v85, 0xffff0000, v142
	v_pk_fma_f32 v[82:83], v[82:83], v[102:103], v[86:87]
	v_mul_f32_e32 v86, 0xbfb8aa3b, v84
	v_mul_f32_e32 v87, 0xbfb8aa3b, v85
	v_exp_f32_e32 v86, v86
	v_exp_f32_e32 v87, v87
	ds_read2_b64 v[138:141], v93 offset0:128 offset1:132
	v_pk_mul_f32 v[100:101], v[100:101], v[92:93] op_sel_hi:[1,0]
	v_add_f32_e32 v86, 1.0, v86
	v_add_f32_e32 v87, 1.0, v87
	v_rcp_f32_e32 v86, v86
	v_rcp_f32_e32 v87, v87
	s_waitcnt lgkmcnt(0)
	v_lshlrev_b32_e32 v146, 16, v138
	v_and_b32_e32 v147, 0xffff0000, v138
	v_pk_fma_f32 v[80:81], v[118:119], v[146:147], v[80:81] op_sel_hi:[0,1,1]
	v_pk_mul_f32 v[84:85], v[86:87], v[84:85]
	v_pk_mul_f32 v[98:99], v[98:99], v[92:93] op_sel_hi:[1,0]
	v_pk_mul_f32 v[80:81], v[84:85], v[80:81]
	v_lshlrev_b32_e32 v84, 16, v143
	v_and_b32_e32 v85, 0xffff0000, v143
	v_mul_f32_e32 v86, 0xbfb8aa3b, v84
	v_mul_f32_e32 v87, 0xbfb8aa3b, v85
	s_waitcnt vmcnt(14)
	v_pk_fma_f32 v[72:73], v[72:73], v[100:101], v[76:77]
	v_lshlrev_b32_e32 v76, 16, v144
	v_and_b32_e32 v77, 0xffff0000, v144
	v_exp_f32_e32 v86, v86
	v_exp_f32_e32 v87, v87
	v_pk_fma_f32 v[74:75], v[74:75], v[98:99], v[78:79]
	v_mul_f32_e32 v78, 0xbfb8aa3b, v76
	v_mul_f32_e32 v79, 0xbfb8aa3b, v77
	v_exp_f32_e32 v78, v78
	v_exp_f32_e32 v79, v79
	v_add_f32_e32 v86, 1.0, v86
	v_add_f32_e32 v87, 1.0, v87
	v_rcp_f32_e32 v86, v86
	v_rcp_f32_e32 v87, v87
	v_add_f32_e32 v78, 1.0, v78
	v_add_f32_e32 v79, 1.0, v79
	v_rcp_f32_e32 v78, v78
	v_rcp_f32_e32 v79, v79
	v_pk_mul_f32 v[84:85], v[86:87], v[84:85]
	v_lshlrev_b32_e32 v86, 16, v140
	v_and_b32_e32 v87, 0xffff0000, v140
	v_pk_fma_f32 v[72:73], v[118:119], v[86:87], v[72:73] op_sel_hi:[0,1,1]
	v_pk_mul_f32 v[76:77], v[78:79], v[76:77]
	v_lshlrev_b32_e32 v138, 16, v139
	v_pk_mul_f32 v[72:73], v[76:77], v[72:73]
	v_lshlrev_b32_e32 v76, 16, v145
	v_and_b32_e32 v77, 0xffff0000, v145
	v_mul_f32_e32 v78, 0xbfb8aa3b, v76
	v_mul_f32_e32 v79, 0xbfb8aa3b, v77
	v_exp_f32_e32 v78, v78
	v_exp_f32_e32 v79, v79
	v_and_b32_e32 v139, 0xffff0000, v139
	v_lshlrev_b32_e32 v102, 16, v141
	v_add_f32_e32 v78, 1.0, v78
	v_add_f32_e32 v79, 1.0, v79
	v_rcp_f32_e32 v78, v78
	v_rcp_f32_e32 v79, v79
	v_and_b32_e32 v103, 0xffff0000, v141
	v_pk_fma_f32 v[82:83], v[118:119], v[138:139], v[82:83] op_sel_hi:[0,1,1]
	v_pk_fma_f32 v[74:75], v[118:119], v[102:103], v[74:75] op_sel_hi:[0,1,1]
	v_pk_mul_f32 v[76:77], v[78:79], v[76:77]
	v_pk_mul_f32 v[82:83], v[84:85], v[82:83]
	v_pk_mul_f32 v[74:75], v[76:77], v[74:75]
	v_cvt_pk_bf16_f32 v84, v80, v81
	v_cvt_pk_bf16_f32 v85, v82, v83
	v_cvt_pk_bf16_f32 v72, v72, v73
	v_cvt_pk_bf16_f32 v73, v74, v75
	ds_read2_b64 v[80:83], v93 offset0:136 offset1:140
	ds_write2_b64 v106, v[84:85], v[72:73] offset1:4
	ds_read2_b64 v[72:75], v137 offset0:8 offset1:12
	v_pk_mul_f32 v[84:85], v[96:97], v[92:93] op_sel_hi:[1,0]
	s_waitcnt lgkmcnt(2)
	v_lshlrev_b32_e32 v76, 16, v80
	v_and_b32_e32 v77, 0xffff0000, v80
	v_lshlrev_b32_e32 v78, 16, v81
	v_and_b32_e32 v79, 0xffff0000, v81
	v_pk_mul_f32 v[80:81], v[94:95], v[92:93] op_sel_hi:[1,0]
	s_waitcnt vmcnt(14)
	v_pk_fma_f32 v[64:65], v[64:65], v[84:85], v[68:69]
	s_waitcnt lgkmcnt(0)
	v_lshlrev_b32_e32 v68, 16, v72
	v_and_b32_e32 v69, 0xffff0000, v72
	v_pk_fma_f32 v[66:67], v[66:67], v[80:81], v[70:71]
	v_mul_f32_e32 v70, 0xbfb8aa3b, v68
	v_mul_f32_e32 v71, 0xbfb8aa3b, v69
	v_exp_f32_e32 v70, v70
	v_exp_f32_e32 v71, v71
	v_pk_fma_f32 v[64:65], v[118:119], v[76:77], v[64:65] op_sel_hi:[0,1,1]
	v_pk_fma_f32 v[66:67], v[118:119], v[78:79], v[66:67] op_sel_hi:[0,1,1]
	v_add_f32_e32 v70, 1.0, v70
	v_add_f32_e32 v71, 1.0, v71
	v_rcp_f32_e32 v70, v70
	v_rcp_f32_e32 v71, v71
	s_nop 0
	v_pk_mul_f32 v[68:69], v[70:71], v[68:69]
	s_nop 0
	v_pk_mul_f32 v[64:65], v[68:69], v[64:65]
	v_lshlrev_b32_e32 v68, 16, v73
	v_and_b32_e32 v69, 0xffff0000, v73
	v_mul_f32_e32 v70, 0xbfb8aa3b, v68
	v_mul_f32_e32 v71, 0xbfb8aa3b, v69
	v_exp_f32_e32 v70, v70
	v_exp_f32_e32 v71, v71
	v_pk_mul_f32 v[72:73], v[88:89], v[92:93] op_sel_hi:[1,0]
	v_cvt_pk_bf16_f32 v64, v64, v65
	v_add_f32_e32 v70, 1.0, v70
	v_add_f32_e32 v71, 1.0, v71
	v_rcp_f32_e32 v70, v70
	v_rcp_f32_e32 v71, v71
	s_waitcnt vmcnt(14)
	v_pk_fma_f32 v[56:57], v[56:57], v[72:73], v[60:61]
	v_lshlrev_b32_e32 v60, 16, v74
	v_and_b32_e32 v61, 0xffff0000, v74
	v_pk_mul_f32 v[68:69], v[70:71], v[68:69]
	v_pk_mul_f32 v[70:71], v[90:91], v[92:93] op_sel_hi:[1,0]
	v_pk_mul_f32 v[66:67], v[68:69], v[66:67]
	v_pk_fma_f32 v[58:59], v[58:59], v[70:71], v[62:63]
	v_mul_f32_e32 v62, 0xbfb8aa3b, v60
	v_mul_f32_e32 v63, 0xbfb8aa3b, v61
	v_exp_f32_e32 v62, v62
	v_exp_f32_e32 v63, v63
	v_cvt_pk_bf16_f32 v65, v66, v67
	v_lshlrev_b32_e32 v66, 16, v82
	v_add_f32_e32 v62, 1.0, v62
	v_add_f32_e32 v63, 1.0, v63
	v_rcp_f32_e32 v62, v62
	v_rcp_f32_e32 v63, v63
	v_and_b32_e32 v67, 0xffff0000, v82
	v_pk_fma_f32 v[56:57], v[118:119], v[66:67], v[56:57] op_sel_hi:[0,1,1]
	v_lshlrev_b32_e32 v68, 16, v83
	v_pk_mul_f32 v[60:61], v[62:63], v[60:61]
	v_and_b32_e32 v69, 0xffff0000, v83
	v_pk_mul_f32 v[56:57], v[60:61], v[56:57]
	v_lshlrev_b32_e32 v60, 16, v75
	v_and_b32_e32 v61, 0xffff0000, v75
	v_mul_f32_e32 v62, 0xbfb8aa3b, v60
	v_mul_f32_e32 v63, 0xbfb8aa3b, v61
	v_exp_f32_e32 v62, v62
	v_exp_f32_e32 v63, v63
	v_pk_fma_f32 v[58:59], v[118:119], v[68:69], v[58:59] op_sel_hi:[0,1,1]
	v_cvt_pk_bf16_f32 v56, v56, v57
	v_add_f32_e32 v62, 1.0, v62
	v_add_f32_e32 v63, 1.0, v63
	v_rcp_f32_e32 v62, v62
	v_rcp_f32_e32 v63, v63
	s_nop 0
	v_pk_mul_f32 v[60:61], v[62:63], v[60:61]
	s_nop 0
	v_pk_mul_f32 v[58:59], v[60:61], v[58:59]
	v_or_b32_e32 v60, v135, v111
	v_cvt_pk_bf16_f32 v57, v58, v59
	ds_write2_b64 v106, v[64:65], v[56:57] offset0:8 offset1:12
	s_waitcnt lgkmcnt(0)
	s_barrier
; #define LDS_BARRIER() do { asm volatile("s_waitcnt lgkmcnt(0)" ::: "memory"); __builtin_amdgcn_s_barrier(); asm volatile("" ::: "memory"); } while (0)
; __device__ __forceinline__ void phase_out(const Params& p, unsigned char* shm) {
;     ...
;         LDS_BARRIER();
; #pragma unroll
;         for (int i = 0; i < 2; ++i) { const int r = crow + 32 * i; *(u32x4*)(p.ACT + (size_t)(row0 + r) * DM + 1024 + h * 64 + cseg) = *(const u32x4*)(YVt + r * LD + cseg); }
;         LDS_BARRIER();
	s_load_dwordx2 s[8:9], s[0:1], 0xc8
	ds_read_b128 v[56:59], v125 offset:36864
	v_ashrrev_i32_e32 v61, 31, v60
	v_lshlrev_b64 v[60:61], 12, v[60:61]
	v_lshlrev_b32_e32 v106, 7, v136
	s_waitcnt lgkmcnt(0)
	v_lshl_add_u64 v[60:61], s[8:9], 0, v[60:61]
	v_lshl_add_u64 v[60:61], v[60:61], 0, v[106:107]
	v_lshl_add_u64 v[60:61], v[60:61], 0, v[116:117]
	global_store_dwordx4 v[60:61], v[56:59], off offset:2048
	v_or_b32_e32 v60, v135, v105
	ds_read_b128 v[56:59], v125 offset:41472
	v_ashrrev_i32_e32 v61, 31, v60
	v_lshlrev_b64 v[60:61], 12, v[60:61]
	v_lshl_add_u64 v[60:61], s[8:9], 0, v[60:61]
	v_lshl_add_u64 v[60:61], v[60:61], 0, v[106:107]
	v_lshl_add_u64 v[60:61], v[60:61], 0, v[116:117]
	s_waitcnt lgkmcnt(0)
	global_store_dwordx4 v[60:61], v[56:59], off offset:2048
	s_waitcnt lgkmcnt(0)
	s_barrier
	s_mov_b32 s8, s24
	s_cbranch_vccnz .LBB0_498
